# v95 plus P8 hid stores widened to 16 bytes (permlane16_swap) and write-through only on a workgroup's last tile, so the P8->P9 write-back has nothing to flush while earlier tile transitions keep fast L
# speedup vs baseline: 1.0148x; 1.0148x over previous
.Lp8_nonext:
	v_lshl_add_u32 v214, s8, 8, v146
	v_lshl_or_b32 v215, s0, 7, v148
	v_mul_u32_u24_e32 v154, 0x1600, v214
	v_lshl_add_u32 v154, v215, 1, v154
	v_bfe_u32 v216, v254, 4, 1
	v_mul_u32_u24_e32 v216, 0x78, v216
	v_add_u32_e32 v154, v154, v216
	v_add_u32_e32 v155, 0x16000, v154
	v_add_u32_e32 v156, 0x2c000, v154
	v_add_u32_e32 v157, 0x42000, v154
	v_add_u32_e32 v158, 0xb0000, v154
	v_add_u32_e32 v159, 0xc6000, v154
	v_add_u32_e32 v160, 0xdc000, v154
	v_add_u32_e32 v161, 0xf2000, v154
	s_waitcnt lgkmcnt(0)
	v_add_f32_e32 v174, v174, v175
	v_add_f32_e32 v178, v178, v179
	v_add_f32_e32 v182, v182, v183
	v_add_f32_e32 v186, v186, v187
	v_add_f32_e32 v190, v190, v191
	v_add_f32_e32 v194, v194, v195
	v_add_f32_e32 v198, v198, v199
	v_add_f32_e32 v202, v202, v203
	v_add_f32_e32 v174, v174, v176
	v_add_f32_e32 v178, v178, v180
	v_add_f32_e32 v182, v182, v184
	v_add_f32_e32 v186, v186, v188
	v_add_f32_e32 v190, v190, v192
	v_add_f32_e32 v194, v194, v196
	v_add_f32_e32 v198, v198, v200
	v_add_f32_e32 v202, v202, v204
	v_add_f32_e32 v174, v174, v177
	v_add_f32_e32 v178, v178, v181
	v_add_f32_e32 v182, v182, v185
	v_add_f32_e32 v186, v186, v189
	v_add_f32_e32 v190, v190, v193
	v_add_f32_e32 v194, v194, v197
	v_add_f32_e32 v198, v198, v201
	v_add_f32_e32 v202, v202, v205
	v_fmamk_f32 v174, v174, 0x3a800000, v152
	v_fmamk_f32 v178, v178, 0x3a800000, v152
	v_fmamk_f32 v182, v182, 0x3a800000, v152
	v_fmamk_f32 v186, v186, 0x3a800000, v152
	v_fmamk_f32 v190, v190, 0x3a800000, v152
	v_fmamk_f32 v194, v194, 0x3a800000, v152
	v_fmamk_f32 v198, v198, 0x3a800000, v152
	v_fmamk_f32 v202, v202, 0x3a800000, v152
	v_mul_f32_e32 v175, 0x4b800000, v174
	v_mul_f32_e32 v179, 0x4b800000, v178
	v_mul_f32_e32 v183, 0x4b800000, v182
	v_mul_f32_e32 v187, 0x4b800000, v186
	v_mul_f32_e32 v191, 0x4b800000, v190
	v_mul_f32_e32 v195, 0x4b800000, v194
	v_mul_f32_e32 v199, 0x4b800000, v198
	v_mul_f32_e32 v203, 0x4b800000, v202
	v_cmp_gt_f32_e64 s[74:75], s58, v174
	v_cmp_gt_f32_e64 s[76:77], s58, v178
	v_cmp_gt_f32_e64 s[78:79], s58, v182
	v_cmp_gt_f32_e64 s[80:81], s58, v186
	v_cmp_gt_f32_e64 s[82:83], s58, v190
	v_cmp_gt_f32_e64 s[84:85], s58, v194
	v_cmp_gt_f32_e64 s[86:87], s58, v198
	v_cmp_gt_f32_e64 s[88:89], s58, v202
	v_cndmask_b32_e64 v174, v174, v175, s[74:75]
	v_cndmask_b32_e64 v178, v178, v179, s[76:77]
	v_cndmask_b32_e64 v182, v182, v183, s[78:79]
	v_cndmask_b32_e64 v186, v186, v187, s[80:81]
	v_cndmask_b32_e64 v190, v190, v191, s[82:83]
	v_cndmask_b32_e64 v194, v194, v195, s[84:85]
	v_cndmask_b32_e64 v198, v198, v199, s[86:87]
	v_cndmask_b32_e64 v202, v202, v203, s[88:89]
	v_rsq_f32_e32 v174, v174
	v_rsq_f32_e32 v178, v178
	v_rsq_f32_e32 v182, v182
	v_rsq_f32_e32 v186, v186
	v_rsq_f32_e32 v190, v190
	v_rsq_f32_e32 v194, v194
	v_rsq_f32_e32 v198, v198
	v_rsq_f32_e32 v202, v202
	v_mul_f32_e32 v175, 0x45800000, v174
	v_mul_f32_e32 v179, 0x45800000, v178
	v_mul_f32_e32 v183, 0x45800000, v182
	v_mul_f32_e32 v187, 0x45800000, v186
	v_mul_f32_e32 v191, 0x45800000, v190
	v_mul_f32_e32 v195, 0x45800000, v194
	v_mul_f32_e32 v199, 0x45800000, v198
	v_mul_f32_e32 v203, 0x45800000, v202
	v_cndmask_b32_e64 v206, v174, v175, s[74:75]
	v_cndmask_b32_e64 v207, v178, v179, s[76:77]
	v_cndmask_b32_e64 v208, v182, v183, s[78:79]
	v_cndmask_b32_e64 v209, v186, v187, s[80:81]
	v_cndmask_b32_e64 v210, v190, v191, s[82:83]
	v_cndmask_b32_e64 v211, v194, v195, s[84:85]
	v_cndmask_b32_e64 v212, v198, v199, s[86:87]
	v_cndmask_b32_e64 v213, v202, v203, s[88:89]
	s_mov_b32 s90, 0xbfb8aa3b
	s_cmp_eq_u64 s[6:7], 0
	v_pk_mul_f32 v[120:121], v[120:121], v[206:207] op_sel_hi:[1,0]
	v_pk_mul_f32 v[122:123], v[122:123], v[206:207] op_sel_hi:[1,0]
	v_pk_mul_f32 v[116:117], v[116:117], v[206:207] op_sel_hi:[1,0]
	v_pk_mul_f32 v[118:119], v[118:119], v[206:207] op_sel_hi:[1,0]
	v_pk_mul_f32 v[124:125], v[124:125], v[206:207] op_sel_hi:[1,0]
	v_pk_mul_f32 v[126:127], v[126:127], v[206:207] op_sel_hi:[1,0]
	v_pk_mul_f32 v[112:113], v[112:113], v[206:207] op_sel_hi:[1,0]
	v_pk_mul_f32 v[114:115], v[114:115], v[206:207] op_sel_hi:[1,0]
	v_pk_mul_f32 v[174:175], v[120:121], s[90:91] op_sel_hi:[1,0]
	v_pk_mul_f32 v[176:177], v[122:123], s[90:91] op_sel_hi:[1,0]
	v_pk_mul_f32 v[178:179], v[116:117], s[90:91] op_sel_hi:[1,0]
	v_pk_mul_f32 v[180:181], v[118:119], s[90:91] op_sel_hi:[1,0]
	v_exp_f32_e32 v174, v174
	v_exp_f32_e32 v175, v175
	v_exp_f32_e32 v176, v176
	v_exp_f32_e32 v177, v177
	v_exp_f32_e32 v178, v178
	v_exp_f32_e32 v179, v179
	v_exp_f32_e32 v180, v180
	v_exp_f32_e32 v181, v181
	v_pk_add_f32 v[174:175], v[174:175], 1.0 op_sel_hi:[1,0]
	v_pk_add_f32 v[176:177], v[176:177], 1.0 op_sel_hi:[1,0]
	v_pk_add_f32 v[178:179], v[178:179], 1.0 op_sel_hi:[1,0]
	v_pk_add_f32 v[180:181], v[180:181], 1.0 op_sel_hi:[1,0]
	v_rcp_f32_e32 v174, v174
	v_rcp_f32_e32 v175, v175
	v_rcp_f32_e32 v176, v176
	v_rcp_f32_e32 v177, v177
	v_rcp_f32_e32 v178, v178
	v_rcp_f32_e32 v179, v179
	v_rcp_f32_e32 v180, v180
	v_rcp_f32_e32 v181, v181
	v_pk_mul_f32 v[120:121], v[120:121], v[174:175]
	v_pk_mul_f32 v[122:123], v[122:123], v[176:177]
	v_pk_mul_f32 v[116:117], v[116:117], v[178:179]
	v_pk_mul_f32 v[118:119], v[118:119], v[180:181]
	v_pk_mul_f32 v[120:121], v[124:125], v[120:121]
	v_pk_mul_f32 v[122:123], v[126:127], v[122:123]
	v_pk_mul_f32 v[116:117], v[112:113], v[116:117]
	v_pk_mul_f32 v[118:119], v[114:115], v[118:119]
	v_cvt_pk_bf16_f32 v120, v120, v121
	v_cvt_pk_bf16_f32 v121, v122, v123
	v_cvt_pk_bf16_f32 v122, v116, v117
	v_cvt_pk_bf16_f32 v123, v118, v119
	s_nop 1
	v_permlane16_swap_b32 v120, v122
	v_permlane16_swap_b32 v121, v123
	s_cbranch_scc1 .Lp8wt0
	global_store_dwordx4 v154, v[120:123], s[34:35]
	s_branch .Lp8st0
.Lp8wt0:
	global_store_dwordx4 v154, v[120:123], s[34:35] sc1
.Lp8st0:
	v_pk_mul_f32 v[108:109], v[108:109], v[206:207] op_sel:[0,1] op_sel_hi:[1,1]
	v_pk_mul_f32 v[110:111], v[110:111], v[206:207] op_sel:[0,1] op_sel_hi:[1,1]
	v_pk_mul_f32 v[100:101], v[100:101], v[206:207] op_sel:[0,1] op_sel_hi:[1,1]
	v_pk_mul_f32 v[102:103], v[102:103], v[206:207] op_sel:[0,1] op_sel_hi:[1,1]
	v_pk_mul_f32 v[104:105], v[104:105], v[206:207] op_sel:[0,1] op_sel_hi:[1,1]
	v_pk_mul_f32 v[106:107], v[106:107], v[206:207] op_sel:[0,1] op_sel_hi:[1,1]
	v_pk_mul_f32 v[96:97], v[96:97], v[206:207] op_sel:[0,1] op_sel_hi:[1,1]
	v_pk_mul_f32 v[98:99], v[98:99], v[206:207] op_sel:[0,1] op_sel_hi:[1,1]
	v_pk_mul_f32 v[174:175], v[108:109], s[90:91] op_sel_hi:[1,0]
	v_pk_mul_f32 v[176:177], v[110:111], s[90:91] op_sel_hi:[1,0]
	v_pk_mul_f32 v[178:179], v[100:101], s[90:91] op_sel_hi:[1,0]
	v_pk_mul_f32 v[180:181], v[102:103], s[90:91] op_sel_hi:[1,0]
	v_exp_f32_e32 v174, v174
	v_exp_f32_e32 v175, v175
	v_exp_f32_e32 v176, v176
	v_exp_f32_e32 v177, v177
	v_exp_f32_e32 v178, v178
	v_exp_f32_e32 v179, v179
	v_exp_f32_e32 v180, v180
	v_exp_f32_e32 v181, v181
	v_pk_add_f32 v[174:175], v[174:175], 1.0 op_sel_hi:[1,0]
	v_pk_add_f32 v[176:177], v[176:177], 1.0 op_sel_hi:[1,0]
	v_pk_add_f32 v[178:179], v[178:179], 1.0 op_sel_hi:[1,0]
	v_pk_add_f32 v[180:181], v[180:181], 1.0 op_sel_hi:[1,0]
	v_rcp_f32_e32 v174, v174
	v_rcp_f32_e32 v175, v175
	v_rcp_f32_e32 v176, v176
	v_rcp_f32_e32 v177, v177
	v_rcp_f32_e32 v178, v178
	v_rcp_f32_e32 v179, v179
	v_rcp_f32_e32 v180, v180
	v_rcp_f32_e32 v181, v181
	v_pk_mul_f32 v[108:109], v[108:109], v[174:175]
	v_pk_mul_f32 v[110:111], v[110:111], v[176:177]
	v_pk_mul_f32 v[100:101], v[100:101], v[178:179]
	v_pk_mul_f32 v[102:103], v[102:103], v[180:181]
	v_pk_mul_f32 v[108:109], v[104:105], v[108:109]
	v_pk_mul_f32 v[110:111], v[106:107], v[110:111]
	v_pk_mul_f32 v[100:101], v[96:97], v[100:101]
	v_pk_mul_f32 v[102:103], v[98:99], v[102:103]
	v_cvt_pk_bf16_f32 v108, v108, v109
	v_cvt_pk_bf16_f32 v109, v110, v111
	v_cvt_pk_bf16_f32 v110, v100, v101
	v_cvt_pk_bf16_f32 v111, v102, v103
	s_nop 1
	v_permlane16_swap_b32 v108, v110
	v_permlane16_swap_b32 v109, v111
	s_cbranch_scc1 .Lp8wt1
	global_store_dwordx4 v155, v[108:111], s[34:35]
	s_branch .Lp8st1
.Lp8wt1:
	global_store_dwordx4 v155, v[108:111], s[34:35] sc1
.Lp8st1:
	v_pk_mul_f32 v[92:93], v[92:93], v[208:209] op_sel_hi:[1,0]
	v_pk_mul_f32 v[94:95], v[94:95], v[208:209] op_sel_hi:[1,0]
	v_pk_mul_f32 v[84:85], v[84:85], v[208:209] op_sel_hi:[1,0]
	v_pk_mul_f32 v[86:87], v[86:87], v[208:209] op_sel_hi:[1,0]
	v_pk_mul_f32 v[88:89], v[88:89], v[208:209] op_sel_hi:[1,0]
	v_pk_mul_f32 v[90:91], v[90:91], v[208:209] op_sel_hi:[1,0]
	v_pk_mul_f32 v[80:81], v[80:81], v[208:209] op_sel_hi:[1,0]
	v_pk_mul_f32 v[82:83], v[82:83], v[208:209] op_sel_hi:[1,0]
	v_pk_mul_f32 v[174:175], v[92:93], s[90:91] op_sel_hi:[1,0]
	v_pk_mul_f32 v[176:177], v[94:95], s[90:91] op_sel_hi:[1,0]
	v_pk_mul_f32 v[178:179], v[84:85], s[90:91] op_sel_hi:[1,0]
	v_pk_mul_f32 v[180:181], v[86:87], s[90:91] op_sel_hi:[1,0]
	v_exp_f32_e32 v174, v174
	v_exp_f32_e32 v175, v175
	v_exp_f32_e32 v176, v176
	v_exp_f32_e32 v177, v177
	v_exp_f32_e32 v178, v178
	v_exp_f32_e32 v179, v179
	v_exp_f32_e32 v180, v180
	v_exp_f32_e32 v181, v181
	v_pk_add_f32 v[174:175], v[174:175], 1.0 op_sel_hi:[1,0]
	v_pk_add_f32 v[176:177], v[176:177], 1.0 op_sel_hi:[1,0]
	v_pk_add_f32 v[178:179], v[178:179], 1.0 op_sel_hi:[1,0]
	v_pk_add_f32 v[180:181], v[180:181], 1.0 op_sel_hi:[1,0]
	v_rcp_f32_e32 v174, v174
	v_rcp_f32_e32 v175, v175
	v_rcp_f32_e32 v176, v176
	v_rcp_f32_e32 v177, v177
	v_rcp_f32_e32 v178, v178
	v_rcp_f32_e32 v179, v179
	v_rcp_f32_e32 v180, v180
	v_rcp_f32_e32 v181, v181
	v_pk_mul_f32 v[92:93], v[92:93], v[174:175]
	v_pk_mul_f32 v[94:95], v[94:95], v[176:177]
	v_pk_mul_f32 v[84:85], v[84:85], v[178:179]
	v_pk_mul_f32 v[86:87], v[86:87], v[180:181]
	v_pk_mul_f32 v[92:93], v[88:89], v[92:93]
	v_pk_mul_f32 v[94:95], v[90:91], v[94:95]
	v_pk_mul_f32 v[84:85], v[80:81], v[84:85]
	v_pk_mul_f32 v[86:87], v[82:83], v[86:87]
	v_cvt_pk_bf16_f32 v92, v92, v93
	v_cvt_pk_bf16_f32 v93, v94, v95
	v_cvt_pk_bf16_f32 v94, v84, v85
	v_cvt_pk_bf16_f32 v95, v86, v87
	s_nop 1
	v_permlane16_swap_b32 v92, v94
	v_permlane16_swap_b32 v93, v95
	s_cbranch_scc1 .Lp8wt2
	global_store_dwordx4 v156, v[92:95], s[34:35]
	s_branch .Lp8st2
.Lp8wt2:
	global_store_dwordx4 v156, v[92:95], s[34:35] sc1
.Lp8st2:
	v_pk_mul_f32 v[76:77], v[76:77], v[208:209] op_sel:[0,1] op_sel_hi:[1,1]
	v_pk_mul_f32 v[78:79], v[78:79], v[208:209] op_sel:[0,1] op_sel_hi:[1,1]
	v_pk_mul_f32 v[68:69], v[68:69], v[208:209] op_sel:[0,1] op_sel_hi:[1,1]
	v_pk_mul_f32 v[70:71], v[70:71], v[208:209] op_sel:[0,1] op_sel_hi:[1,1]
	v_pk_mul_f32 v[72:73], v[72:73], v[208:209] op_sel:[0,1] op_sel_hi:[1,1]
	v_pk_mul_f32 v[74:75], v[74:75], v[208:209] op_sel:[0,1] op_sel_hi:[1,1]
	v_pk_mul_f32 v[64:65], v[64:65], v[208:209] op_sel:[0,1] op_sel_hi:[1,1]
	v_pk_mul_f32 v[66:67], v[66:67], v[208:209] op_sel:[0,1] op_sel_hi:[1,1]
	v_pk_mul_f32 v[174:175], v[76:77], s[90:91] op_sel_hi:[1,0]
	v_pk_mul_f32 v[176:177], v[78:79], s[90:91] op_sel_hi:[1,0]
	v_pk_mul_f32 v[178:179], v[68:69], s[90:91] op_sel_hi:[1,0]
	v_pk_mul_f32 v[180:181], v[70:71], s[90:91] op_sel_hi:[1,0]
	v_exp_f32_e32 v174, v174
	v_exp_f32_e32 v175, v175
	v_exp_f32_e32 v176, v176
	v_exp_f32_e32 v177, v177
	v_exp_f32_e32 v178, v178
	v_exp_f32_e32 v179, v179
	v_exp_f32_e32 v180, v180
	v_exp_f32_e32 v181, v181
	v_pk_add_f32 v[174:175], v[174:175], 1.0 op_sel_hi:[1,0]
	v_pk_add_f32 v[176:177], v[176:177], 1.0 op_sel_hi:[1,0]
	v_pk_add_f32 v[178:179], v[178:179], 1.0 op_sel_hi:[1,0]
	v_pk_add_f32 v[180:181], v[180:181], 1.0 op_sel_hi:[1,0]
	v_rcp_f32_e32 v174, v174
	v_rcp_f32_e32 v175, v175
	v_rcp_f32_e32 v176, v176
	v_rcp_f32_e32 v177, v177
	v_rcp_f32_e32 v178, v178
	v_rcp_f32_e32 v179, v179
	v_rcp_f32_e32 v180, v180
	v_rcp_f32_e32 v181, v181
	v_pk_mul_f32 v[76:77], v[76:77], v[174:175]
	v_pk_mul_f32 v[78:79], v[78:79], v[176:177]
	v_pk_mul_f32 v[68:69], v[68:69], v[178:179]
	v_pk_mul_f32 v[70:71], v[70:71], v[180:181]
	v_pk_mul_f32 v[76:77], v[72:73], v[76:77]
	v_pk_mul_f32 v[78:79], v[74:75], v[78:79]
	v_pk_mul_f32 v[68:69], v[64:65], v[68:69]
	v_pk_mul_f32 v[70:71], v[66:67], v[70:71]
	v_cvt_pk_bf16_f32 v76, v76, v77
	v_cvt_pk_bf16_f32 v77, v78, v79
	v_cvt_pk_bf16_f32 v78, v68, v69
	v_cvt_pk_bf16_f32 v79, v70, v71
	s_nop 1
	v_permlane16_swap_b32 v76, v78
	v_permlane16_swap_b32 v77, v79
	s_cbranch_scc1 .Lp8wt3
	global_store_dwordx4 v157, v[76:79], s[34:35]
	s_branch .Lp8st3
.Lp8wt3:
	global_store_dwordx4 v157, v[76:79], s[34:35] sc1
.Lp8st3:
	v_pk_mul_f32 v[60:61], v[60:61], v[210:211] op_sel_hi:[1,0]
	v_pk_mul_f32 v[62:63], v[62:63], v[210:211] op_sel_hi:[1,0]
	v_pk_mul_f32 v[52:53], v[52:53], v[210:211] op_sel_hi:[1,0]
	v_pk_mul_f32 v[54:55], v[54:55], v[210:211] op_sel_hi:[1,0]
	v_pk_mul_f32 v[56:57], v[56:57], v[210:211] op_sel_hi:[1,0]
	v_pk_mul_f32 v[58:59], v[58:59], v[210:211] op_sel_hi:[1,0]
	v_pk_mul_f32 v[48:49], v[48:49], v[210:211] op_sel_hi:[1,0]
	v_pk_mul_f32 v[50:51], v[50:51], v[210:211] op_sel_hi:[1,0]
	v_pk_mul_f32 v[174:175], v[60:61], s[90:91] op_sel_hi:[1,0]
	v_pk_mul_f32 v[176:177], v[62:63], s[90:91] op_sel_hi:[1,0]
	v_pk_mul_f32 v[178:179], v[52:53], s[90:91] op_sel_hi:[1,0]
	v_pk_mul_f32 v[180:181], v[54:55], s[90:91] op_sel_hi:[1,0]
	v_exp_f32_e32 v174, v174
	v_exp_f32_e32 v175, v175
	v_exp_f32_e32 v176, v176
	v_exp_f32_e32 v177, v177
	v_exp_f32_e32 v178, v178
	v_exp_f32_e32 v179, v179
	v_exp_f32_e32 v180, v180
	v_exp_f32_e32 v181, v181
	v_pk_add_f32 v[174:175], v[174:175], 1.0 op_sel_hi:[1,0]
	v_pk_add_f32 v[176:177], v[176:177], 1.0 op_sel_hi:[1,0]
	v_pk_add_f32 v[178:179], v[178:179], 1.0 op_sel_hi:[1,0]
	v_pk_add_f32 v[180:181], v[180:181], 1.0 op_sel_hi:[1,0]
	v_rcp_f32_e32 v174, v174
	v_rcp_f32_e32 v175, v175
	v_rcp_f32_e32 v176, v176
	v_rcp_f32_e32 v177, v177
	v_rcp_f32_e32 v178, v178
	v_rcp_f32_e32 v179, v179
	v_rcp_f32_e32 v180, v180
	v_rcp_f32_e32 v181, v181
	v_pk_mul_f32 v[60:61], v[60:61], v[174:175]
	v_pk_mul_f32 v[62:63], v[62:63], v[176:177]
	v_pk_mul_f32 v[52:53], v[52:53], v[178:179]
	v_pk_mul_f32 v[54:55], v[54:55], v[180:181]
	v_pk_mul_f32 v[60:61], v[56:57], v[60:61]
	v_pk_mul_f32 v[62:63], v[58:59], v[62:63]
	v_pk_mul_f32 v[52:53], v[48:49], v[52:53]
	v_pk_mul_f32 v[54:55], v[50:51], v[54:55]
	v_cvt_pk_bf16_f32 v60, v60, v61
	v_cvt_pk_bf16_f32 v61, v62, v63
	v_cvt_pk_bf16_f32 v62, v52, v53
	v_cvt_pk_bf16_f32 v63, v54, v55
	s_nop 1
	v_permlane16_swap_b32 v60, v62
	v_permlane16_swap_b32 v61, v63
	s_cbranch_scc1 .Lp8wt4
	global_store_dwordx4 v158, v[60:63], s[34:35]
	s_branch .Lp8st4
.Lp8wt4:
	global_store_dwordx4 v158, v[60:63], s[34:35] sc1
.Lp8st4:
	v_pk_mul_f32 v[44:45], v[44:45], v[210:211] op_sel:[0,1] op_sel_hi:[1,1]
	v_pk_mul_f32 v[46:47], v[46:47], v[210:211] op_sel:[0,1] op_sel_hi:[1,1]
	v_pk_mul_f32 v[36:37], v[36:37], v[210:211] op_sel:[0,1] op_sel_hi:[1,1]
	v_pk_mul_f32 v[38:39], v[38:39], v[210:211] op_sel:[0,1] op_sel_hi:[1,1]
	v_pk_mul_f32 v[40:41], v[40:41], v[210:211] op_sel:[0,1] op_sel_hi:[1,1]
	v_pk_mul_f32 v[42:43], v[42:43], v[210:211] op_sel:[0,1] op_sel_hi:[1,1]
	v_pk_mul_f32 v[32:33], v[32:33], v[210:211] op_sel:[0,1] op_sel_hi:[1,1]
	v_pk_mul_f32 v[34:35], v[34:35], v[210:211] op_sel:[0,1] op_sel_hi:[1,1]
	v_pk_mul_f32 v[174:175], v[44:45], s[90:91] op_sel_hi:[1,0]
	v_pk_mul_f32 v[176:177], v[46:47], s[90:91] op_sel_hi:[1,0]
	v_pk_mul_f32 v[178:179], v[36:37], s[90:91] op_sel_hi:[1,0]
	v_pk_mul_f32 v[180:181], v[38:39], s[90:91] op_sel_hi:[1,0]
	v_exp_f32_e32 v174, v174
	v_exp_f32_e32 v175, v175
	v_exp_f32_e32 v176, v176
	v_exp_f32_e32 v177, v177
	v_exp_f32_e32 v178, v178
	v_exp_f32_e32 v179, v179
	v_exp_f32_e32 v180, v180
	v_exp_f32_e32 v181, v181
	v_pk_add_f32 v[174:175], v[174:175], 1.0 op_sel_hi:[1,0]
	v_pk_add_f32 v[176:177], v[176:177], 1.0 op_sel_hi:[1,0]
	v_pk_add_f32 v[178:179], v[178:179], 1.0 op_sel_hi:[1,0]
	v_pk_add_f32 v[180:181], v[180:181], 1.0 op_sel_hi:[1,0]
	v_rcp_f32_e32 v174, v174
	v_rcp_f32_e32 v175, v175
	v_rcp_f32_e32 v176, v176
	v_rcp_f32_e32 v177, v177
	v_rcp_f32_e32 v178, v178
	v_rcp_f32_e32 v179, v179
	v_rcp_f32_e32 v180, v180
	v_rcp_f32_e32 v181, v181
	v_pk_mul_f32 v[44:45], v[44:45], v[174:175]
	v_pk_mul_f32 v[46:47], v[46:47], v[176:177]
	v_pk_mul_f32 v[36:37], v[36:37], v[178:179]
	v_pk_mul_f32 v[38:39], v[38:39], v[180:181]
	v_pk_mul_f32 v[44:45], v[40:41], v[44:45]
	v_pk_mul_f32 v[46:47], v[42:43], v[46:47]
	v_pk_mul_f32 v[36:37], v[32:33], v[36:37]
	v_pk_mul_f32 v[38:39], v[34:35], v[38:39]
	v_cvt_pk_bf16_f32 v44, v44, v45
	v_cvt_pk_bf16_f32 v45, v46, v47
	v_cvt_pk_bf16_f32 v46, v36, v37
	v_cvt_pk_bf16_f32 v47, v38, v39
	s_nop 1
	v_permlane16_swap_b32 v44, v46
	v_permlane16_swap_b32 v45, v47
	s_cbranch_scc1 .Lp8wt5
	global_store_dwordx4 v159, v[44:47], s[34:35]
	s_branch .Lp8st5
.Lp8wt5:
	global_store_dwordx4 v159, v[44:47], s[34:35] sc1
.Lp8st5:
	v_pk_mul_f32 v[28:29], v[28:29], v[212:213] op_sel_hi:[1,0]
	v_pk_mul_f32 v[30:31], v[30:31], v[212:213] op_sel_hi:[1,0]
	v_pk_mul_f32 v[20:21], v[20:21], v[212:213] op_sel_hi:[1,0]
	v_pk_mul_f32 v[22:23], v[22:23], v[212:213] op_sel_hi:[1,0]
	v_pk_mul_f32 v[24:25], v[24:25], v[212:213] op_sel_hi:[1,0]
	v_pk_mul_f32 v[26:27], v[26:27], v[212:213] op_sel_hi:[1,0]
	v_pk_mul_f32 v[16:17], v[16:17], v[212:213] op_sel_hi:[1,0]
	v_pk_mul_f32 v[18:19], v[18:19], v[212:213] op_sel_hi:[1,0]
	v_pk_mul_f32 v[174:175], v[28:29], s[90:91] op_sel_hi:[1,0]
	v_pk_mul_f32 v[176:177], v[30:31], s[90:91] op_sel_hi:[1,0]
	v_pk_mul_f32 v[178:179], v[20:21], s[90:91] op_sel_hi:[1,0]
	v_pk_mul_f32 v[180:181], v[22:23], s[90:91] op_sel_hi:[1,0]
	v_exp_f32_e32 v174, v174
	v_exp_f32_e32 v175, v175
	v_exp_f32_e32 v176, v176
	v_exp_f32_e32 v177, v177
	v_exp_f32_e32 v178, v178
	v_exp_f32_e32 v179, v179
	v_exp_f32_e32 v180, v180
	v_exp_f32_e32 v181, v181
	v_pk_add_f32 v[174:175], v[174:175], 1.0 op_sel_hi:[1,0]
	v_pk_add_f32 v[176:177], v[176:177], 1.0 op_sel_hi:[1,0]
	v_pk_add_f32 v[178:179], v[178:179], 1.0 op_sel_hi:[1,0]
	v_pk_add_f32 v[180:181], v[180:181], 1.0 op_sel_hi:[1,0]
	v_rcp_f32_e32 v174, v174
	v_rcp_f32_e32 v175, v175
	v_rcp_f32_e32 v176, v176
	v_rcp_f32_e32 v177, v177
	v_rcp_f32_e32 v178, v178
	v_rcp_f32_e32 v179, v179
	v_rcp_f32_e32 v180, v180
	v_rcp_f32_e32 v181, v181
	v_pk_mul_f32 v[28:29], v[28:29], v[174:175]
	v_pk_mul_f32 v[30:31], v[30:31], v[176:177]
	v_pk_mul_f32 v[20:21], v[20:21], v[178:179]
	v_pk_mul_f32 v[22:23], v[22:23], v[180:181]
	v_pk_mul_f32 v[28:29], v[24:25], v[28:29]
	v_pk_mul_f32 v[30:31], v[26:27], v[30:31]
	v_pk_mul_f32 v[20:21], v[16:17], v[20:21]
	v_pk_mul_f32 v[22:23], v[18:19], v[22:23]
	v_cvt_pk_bf16_f32 v28, v28, v29
	v_cvt_pk_bf16_f32 v29, v30, v31
	v_cvt_pk_bf16_f32 v30, v20, v21
	v_cvt_pk_bf16_f32 v31, v22, v23
	s_nop 1
	v_permlane16_swap_b32 v28, v30
	v_permlane16_swap_b32 v29, v31
	s_cbranch_scc1 .Lp8wt6
	global_store_dwordx4 v160, v[28:31], s[34:35]
	s_branch .Lp8st6
.Lp8wt6:
	global_store_dwordx4 v160, v[28:31], s[34:35] sc1
.Lp8st6:
	v_pk_mul_f32 v[12:13], v[12:13], v[212:213] op_sel:[0,1] op_sel_hi:[1,1]
	v_pk_mul_f32 v[14:15], v[14:15], v[212:213] op_sel:[0,1] op_sel_hi:[1,1]
	v_pk_mul_f32 v[4:5], v[4:5], v[212:213] op_sel:[0,1] op_sel_hi:[1,1]
	v_pk_mul_f32 v[6:7], v[6:7], v[212:213] op_sel:[0,1] op_sel_hi:[1,1]
	v_pk_mul_f32 v[8:9], v[8:9], v[212:213] op_sel:[0,1] op_sel_hi:[1,1]
	v_pk_mul_f32 v[10:11], v[10:11], v[212:213] op_sel:[0,1] op_sel_hi:[1,1]
	v_pk_mul_f32 v[0:1], v[0:1], v[212:213] op_sel:[0,1] op_sel_hi:[1,1]
	v_pk_mul_f32 v[2:3], v[2:3], v[212:213] op_sel:[0,1] op_sel_hi:[1,1]
	v_pk_mul_f32 v[174:175], v[12:13], s[90:91] op_sel_hi:[1,0]
	v_pk_mul_f32 v[176:177], v[14:15], s[90:91] op_sel_hi:[1,0]
	v_pk_mul_f32 v[178:179], v[4:5], s[90:91] op_sel_hi:[1,0]
	v_pk_mul_f32 v[180:181], v[6:7], s[90:91] op_sel_hi:[1,0]
	v_exp_f32_e32 v174, v174
	v_exp_f32_e32 v175, v175
	v_exp_f32_e32 v176, v176
	v_exp_f32_e32 v177, v177
	v_exp_f32_e32 v178, v178
	v_exp_f32_e32 v179, v179
	v_exp_f32_e32 v180, v180
	v_exp_f32_e32 v181, v181
	v_pk_add_f32 v[174:175], v[174:175], 1.0 op_sel_hi:[1,0]
	v_pk_add_f32 v[176:177], v[176:177], 1.0 op_sel_hi:[1,0]
	v_pk_add_f32 v[178:179], v[178:179], 1.0 op_sel_hi:[1,0]
	v_pk_add_f32 v[180:181], v[180:181], 1.0 op_sel_hi:[1,0]
	v_rcp_f32_e32 v174, v174
	v_rcp_f32_e32 v175, v175
	v_rcp_f32_e32 v176, v176
	v_rcp_f32_e32 v177, v177
	v_rcp_f32_e32 v178, v178
	v_rcp_f32_e32 v179, v179
	v_rcp_f32_e32 v180, v180
	v_rcp_f32_e32 v181, v181
	v_pk_mul_f32 v[12:13], v[12:13], v[174:175]
	v_pk_mul_f32 v[14:15], v[14:15], v[176:177]
	v_pk_mul_f32 v[4:5], v[4:5], v[178:179]
	v_pk_mul_f32 v[6:7], v[6:7], v[180:181]
	v_pk_mul_f32 v[12:13], v[8:9], v[12:13]
	v_pk_mul_f32 v[14:15], v[10:11], v[14:15]
	v_pk_mul_f32 v[4:5], v[0:1], v[4:5]
	v_pk_mul_f32 v[6:7], v[2:3], v[6:7]
	v_cvt_pk_bf16_f32 v12, v12, v13
	v_cvt_pk_bf16_f32 v13, v14, v15
	v_cvt_pk_bf16_f32 v14, v4, v5
	v_cvt_pk_bf16_f32 v15, v6, v7
	s_nop 1
	v_permlane16_swap_b32 v12, v14
	v_permlane16_swap_b32 v13, v15
	s_cbranch_scc1 .Lp8wt7
	global_store_dwordx4 v161, v[12:15], s[34:35]
	s_branch .Lp8st7
.Lp8wt7:
	global_store_dwordx4 v161, v[12:15], s[34:35] sc1
.Lp8st7:
	s_andn2_b64 vcc, exec, s[6:7]
	s_mov_b64 s[6:7], -1
	s_cbranch_vccnz .LBB0_543
	s_andn2_b64 vcc, exec, s[14:15]
	s_cbranch_vccnz .LBB0_542
	s_barrier
	s_branch .LBB0_542
